# embed_p4
# speedup vs baseline: 1.0093x; 1.0014x over previous
; #define PG8_STAGE(bufoff, gbase, voff) do { _Pragma("unroll") for (int _i = 0; _i < 2; ++_i) \
;         __builtin_amdgcn_global_load_lds((const unsigned*)((const char*)(gbase) + (voff)[_i]), (LAS unsigned*)(lds + (bufoff) + ldsw + _i * 8192), 16, 0, 0); } while (0)
; #define PG8_LDA(dst, b, h) do { _Pragma("unroll") for (int m = 0; m < 4; ++m) _Pragma("unroll") for (int k = 0; k < 2; ++k) dst[m][k] = *(const LAS bf16x8*)(lds + PG8_SA(b, h) + aoff + m * 2048 + k * 1024); } while (0)
; #define PG8_LDB(dst, b, h) do { _Pragma("unroll") for (int n = 0; n < 2; ++n) _Pragma("unroll") for (int k = 0; k < 2; ++k) dst[n][k] = *(const LAS bf16x8*)(lds + PG8_SB(b, h) + boff + n * 2048 + k * 1024); } while (0)
; #define PG8_MMA(ai, bj, At, Bt) do { __builtin_amdgcn_s_setprio(1); _Pragma("unroll") for (int m = 0; m < 4; ++m) _Pragma("unroll") for (int n = 0; n < 2; ++n) _Pragma("unroll") for (int k = 0; k < 2; ++k) \
;         acc[ai][bj][m][n] = __builtin_amdgcn_mfma_f32_16x16x32_bf16(Bt[n][k], At[m][k], acc[ai][bj][m][n], 0, 0, 0); __builtin_amdgcn_s_setprio(0); } while (0)
; #define PG8_WAIT_L(n) asm volatile("s_waitcnt lgkmcnt(" #n ")" ::: "memory")
; #define PG8_BAR __builtin_amdgcn_s_barrier()
; #define PG8_SCHED __builtin_amdgcn_sched_barrier(0)
; template <class Epi, class Job>
; __device__ __forceinline__ void gemm_phase(LAS unsigned char* lds, const Job& S, const Epi& E) {
;     ...
;         for (int t = 0; t < nt; t += 2) {
;             const bool last = (t == nt - 2);
;             const char* a1 = cA + (size_t)(t + 1) * kstep;
;             const char* a2 = last ? nA : cA + (size_t)(t + 2) * kstep; const char* b2 = last ? nB : cB + (size_t)(t + 2) * kstep;
;             const char* a3 = a2 + kstep; const char* b3 = b2 + kstep;
;             PG8_LDB(B0, 0, 0); PG8_SCHED; PG8_LDA(At, 0, 0); PG8_STAGE(PG8_SA(1, 1), a1 + hstepA, voffA);
;             PG8_WAIT_L(8); PG8_BAR; PG8_WAIT_L(0); PG8_MMA(0, 0, At, B0); PG8_BAR; PG8_SCHED;
;             PG8_LDB(B1, 0, 1); PG8_STAGE(PG8_SB(0, 0), b2, voffB);
;     ...
;         for (int a = 0; a < 2; ++a)
; #pragma unroll
;             for (int b = 0; b < 2; ++b)
; #pragma unroll
;                 for (int m = 0; m < 4; ++m)
; #pragma unroll
;                     for (int n = 0; n < 2; ++n) acc[a][b][m][n] = (f32x4){0.f, 0.f, 0.f, 0.f};
.LBB0_456:
	s_add_u32 s36, s36, 0x100080
	s_addc_u32 s37, s37, 0
	s_add_u32 s79, s46, 0x100
	v_mov_b32_e32 v0, 0
	s_addc_u32 s80, s47, 0
	s_mov_b32 s81, -2
	v_mov_b32_e32 v1, v0
	v_mov_b32_e32 v2, v0
	v_mov_b32_e32 v3, v0
	v_mov_b32_e32 v4, v0
	v_mov_b32_e32 v5, v0
	v_mov_b32_e32 v6, v0
	v_mov_b32_e32 v7, v0
	v_mov_b32_e32 v8, v0
	v_mov_b32_e32 v9, v0
	v_mov_b32_e32 v10, v0
	v_mov_b32_e32 v11, v0
	v_mov_b32_e32 v16, v0
	v_mov_b32_e32 v17, v0
	v_mov_b32_e32 v18, v0
	v_mov_b32_e32 v19, v0
	v_mov_b32_e32 v24, v0
	v_mov_b32_e32 v25, v0
	v_mov_b32_e32 v26, v0
	v_mov_b32_e32 v27, v0
	v_mov_b32_e32 v32, v0
	v_mov_b32_e32 v33, v0
	v_mov_b32_e32 v34, v0
	v_mov_b32_e32 v35, v0
	v_mov_b32_e32 v40, v0
	v_mov_b32_e32 v41, v0
	v_mov_b32_e32 v42, v0
	v_mov_b32_e32 v43, v0
	v_mov_b32_e32 v48, v0
	v_mov_b32_e32 v49, v0
	v_mov_b32_e32 v50, v0
	v_mov_b32_e32 v51, v0
	v_mov_b32_e32 v12, v0
	v_mov_b32_e32 v13, v0
	v_mov_b32_e32 v14, v0
	v_mov_b32_e32 v15, v0
	v_mov_b32_e32 v20, v0
	v_mov_b32_e32 v21, v0
	v_mov_b32_e32 v22, v0
	v_mov_b32_e32 v23, v0
	v_mov_b32_e32 v28, v0
	v_mov_b32_e32 v29, v0
	v_mov_b32_e32 v30, v0
	v_mov_b32_e32 v31, v0
	v_mov_b32_e32 v36, v0
	v_mov_b32_e32 v37, v0
	v_mov_b32_e32 v38, v0
	v_mov_b32_e32 v39, v0
	v_mov_b32_e32 v44, v0
	v_mov_b32_e32 v45, v0
	v_mov_b32_e32 v46, v0
	v_mov_b32_e32 v47, v0
	v_mov_b32_e32 v52, v0
	v_mov_b32_e32 v53, v0
	v_mov_b32_e32 v54, v0
	v_mov_b32_e32 v55, v0
	v_mov_b32_e32 v56, v0
	v_mov_b32_e32 v57, v0
	v_mov_b32_e32 v58, v0
	v_mov_b32_e32 v59, v0
	v_mov_b32_e32 v60, v0
	v_mov_b32_e32 v61, v0
	v_mov_b32_e32 v62, v0
	v_mov_b32_e32 v63, v0
	v_mov_b32_e32 v64, v0
	v_mov_b32_e32 v65, v0
	v_mov_b32_e32 v66, v0
	v_mov_b32_e32 v67, v0
	v_mov_b32_e32 v68, v0
	v_mov_b32_e32 v69, v0
	v_mov_b32_e32 v70, v0
	v_mov_b32_e32 v71, v0
	v_mov_b32_e32 v72, v0
	v_mov_b32_e32 v73, v0
	v_mov_b32_e32 v74, v0
	v_mov_b32_e32 v75, v0
	v_mov_b32_e32 v80, v0
	v_mov_b32_e32 v81, v0
	v_mov_b32_e32 v82, v0
	v_mov_b32_e32 v83, v0
	v_mov_b32_e32 v88, v0
	v_mov_b32_e32 v89, v0
	v_mov_b32_e32 v90, v0
	v_mov_b32_e32 v91, v0
	v_mov_b32_e32 v96, v0
	v_mov_b32_e32 v97, v0
	v_mov_b32_e32 v98, v0
	v_mov_b32_e32 v99, v0
	v_mov_b32_e32 v104, v0
	v_mov_b32_e32 v105, v0
	v_mov_b32_e32 v106, v0
	v_mov_b32_e32 v107, v0
	v_mov_b32_e32 v112, v0
	v_mov_b32_e32 v113, v0
	v_mov_b32_e32 v114, v0
	v_mov_b32_e32 v115, v0
	v_mov_b32_e32 v76, v0
	v_mov_b32_e32 v77, v0
	v_mov_b32_e32 v78, v0
	v_mov_b32_e32 v79, v0
	v_mov_b32_e32 v84, v0
	v_mov_b32_e32 v85, v0
	v_mov_b32_e32 v86, v0
	v_mov_b32_e32 v87, v0
	v_mov_b32_e32 v92, v0
	v_mov_b32_e32 v93, v0
	v_mov_b32_e32 v94, v0
	v_mov_b32_e32 v95, v0
	v_mov_b32_e32 v100, v0
	v_mov_b32_e32 v101, v0
	v_mov_b32_e32 v102, v0
	v_mov_b32_e32 v103, v0
	v_mov_b32_e32 v108, v0
	v_mov_b32_e32 v109, v0
	v_mov_b32_e32 v110, v0
	v_mov_b32_e32 v111, v0
	v_mov_b32_e32 v116, v0
	v_mov_b32_e32 v117, v0
	v_mov_b32_e32 v118, v0
	v_mov_b32_e32 v119, v0
	v_mov_b32_e32 v120, v0
	v_mov_b32_e32 v121, v0
	v_mov_b32_e32 v122, v0
	v_mov_b32_e32 v123, v0
	v_mov_b32_e32 v124, v0
	v_mov_b32_e32 v125, v0
	v_mov_b32_e32 v126, v0
	v_mov_b32_e32 v127, v0
	ds_read_b128 v[154:157], v150
	ds_read_b128 v[158:161], v150 offset:1024
	ds_read_b128 v[162:165], v150 offset:2048
	ds_read_b128 v[166:169], v150 offset:3072
	ds_read_b128 v[170:173], v151
	ds_read_b128 v[178:181], v151 offset:2048
	ds_read_b128 v[186:189], v151 offset:4096
	ds_read_b128 v[194:197], v151 offset:6144
.LBB0_457:
	s_add_u32 s46, s36, 0xfff00080
	s_addc_u32 s47, s37, -1
	s_cmp_eq_u32 s81, 60
	s_cselect_b32 s49, s29, s47
	s_cselect_b32 s48, s28, s46
	s_cselect_b32 s47, s31, s80
	s_cselect_b32 s46, s30, s79
	s_add_i32 m0, s57, 0xc000
	ds_read_b128 v[174:177], v151 offset:1024
	ds_read_b128 v[182:185], v151 offset:3072
	ds_read_b128 v[190:193], v151 offset:5120
	ds_read_b128 v[198:201], v151 offset:7168
	global_load_lds_dwordx4 v132, s[36:37]
	s_add_i32 m0, s57, 0xe000
	s_nop 0
	global_load_lds_dwordx4 v142, s[36:37]
	s_waitcnt lgkmcnt(8)
	s_barrier
	s_waitcnt lgkmcnt(0)
	s_setprio 1
	v_mfma_f32_16x16x32_bf16 v[124:127], v[154:157], v[170:173], v[124:127]
	ds_read_b128 v[202:205], v152
	v_mfma_f32_16x16x32_bf16 v[120:123], v[162:165], v[170:173], v[120:123]
	v_mfma_f32_16x16x32_bf16 v[116:119], v[154:157], v[178:181], v[116:119]
	ds_read_b128 v[206:209], v152 offset:1024
	v_mfma_f32_16x16x32_bf16 v[108:111], v[162:165], v[178:181], v[108:111]
	v_mfma_f32_16x16x32_bf16 v[100:103], v[154:157], v[186:189], v[100:103]
	ds_read_b128 v[210:213], v152 offset:2048
	v_mfma_f32_16x16x32_bf16 v[92:95], v[162:165], v[186:189], v[92:95]
	v_mfma_f32_16x16x32_bf16 v[84:87], v[154:157], v[194:197], v[84:87]
	ds_read_b128 v[214:217], v152 offset:3072
	v_mfma_f32_16x16x32_bf16 v[76:79], v[162:165], v[194:197], v[76:79]
	v_mfma_f32_16x16x32_bf16 v[124:127], v[158:161], v[174:177], v[124:127]
	v_mfma_f32_16x16x32_bf16 v[120:123], v[166:169], v[174:177], v[120:123]
	v_mfma_f32_16x16x32_bf16 v[116:119], v[158:161], v[182:185], v[116:119]
	v_mfma_f32_16x16x32_bf16 v[108:111], v[166:169], v[182:185], v[108:111]
	v_mfma_f32_16x16x32_bf16 v[100:103], v[158:161], v[190:193], v[100:103]
	v_mfma_f32_16x16x32_bf16 v[92:95], v[166:169], v[190:193], v[92:95]
	v_mfma_f32_16x16x32_bf16 v[84:87], v[158:161], v[198:201], v[84:87]
	v_mfma_f32_16x16x32_bf16 v[76:79], v[166:169], v[198:201], v[76:79]
	s_setprio 0
	s_barrier
	s_add_i32 s82, s66, s56
	s_mov_b32 m0, s82
	s_nop 0
	global_load_lds_dwordx4 v136, s[46:47]
	s_add_i32 m0, s82, 0x2000
	s_nop 0
	global_load_lds_dwordx4 v140, s[46:47]
	s_barrier
; #define PG8_STAGE(bufoff, gbase, voff) do { _Pragma("unroll") for (int _i = 0; _i < 2; ++_i) \
;         __builtin_amdgcn_global_load_lds((const unsigned*)((const char*)(gbase) + (voff)[_i]), (LAS unsigned*)(lds + (bufoff) + ldsw + _i * 8192), 16, 0, 0); } while (0)
; #define PG8_LDA(dst, b, h) do { _Pragma("unroll") for (int m = 0; m < 4; ++m) _Pragma("unroll") for (int k = 0; k < 2; ++k) dst[m][k] = *(const LAS bf16x8*)(lds + PG8_SA(b, h) + aoff + m * 2048 + k * 1024); } while (0)
; #define PG8_LDB(dst, b, h) do { _Pragma("unroll") for (int n = 0; n < 2; ++n) _Pragma("unroll") for (int k = 0; k < 2; ++k) dst[n][k] = *(const LAS bf16x8*)(lds + PG8_SB(b, h) + boff + n * 2048 + k * 1024); } while (0)
; #define PG8_MMA(ai, bj, At, Bt) do { __builtin_amdgcn_s_setprio(1); _Pragma("unroll") for (int m = 0; m < 4; ++m) _Pragma("unroll") for (int n = 0; n < 2; ++n) _Pragma("unroll") for (int k = 0; k < 2; ++k) \
;         acc[ai][bj][m][n] = __builtin_amdgcn_mfma_f32_16x16x32_bf16(Bt[n][k], At[m][k], acc[ai][bj][m][n], 0, 0, 0); __builtin_amdgcn_s_setprio(0); } while (0)
; #define PG8_WAIT_V(n) asm volatile("s_waitcnt vmcnt(" #n ")" ::: "memory")
; #define PG8_WAIT_L(n) asm volatile("s_waitcnt lgkmcnt(" #n ")" ::: "memory")
; #define PG8_BAR __builtin_amdgcn_s_barrier()
; #define PG8_SCHED __builtin_amdgcn_sched_barrier(0)
; template <class Epi, class Job>
; __device__ __forceinline__ void gemm_phase(LAS unsigned char* lds, const Job& S, const Epi& E) {
;     ...
;             PG8_BAR; PG8_WAIT_L(0); PG8_MMA(0, 1, At, B1); PG8_BAR;
;             PG8_LDA(At, 0, 1); PG8_STAGE(PG8_SA(0, 0), a2, voffA);
;             PG8_BAR; PG8_WAIT_L(0); PG8_MMA(1, 0, At, B0); PG8_BAR; PG8_SCHED;
;             PG8_STAGE(PG8_SB(0, 1), b2 + hstepB, voffB);
;             PG8_WAIT_V(6); PG8_BAR; PG8_MMA(1, 1, At, B1); PG8_BAR;
;             PG8_LDB(B0, 1, 0); PG8_SCHED; PG8_LDA(At, 1, 0); PG8_STAGE(PG8_SA(0, 1), a2 + hstepA, voffA);
;             PG8_WAIT_L(8); PG8_BAR; PG8_WAIT_L(0); PG8_MMA(0, 0, At, B0); PG8_BAR; PG8_SCHED;
	s_waitcnt lgkmcnt(0)
	s_setprio 1
	v_mfma_f32_16x16x32_bf16 v[112:115], v[202:205], v[170:173], v[112:115]
	v_mfma_f32_16x16x32_bf16 v[104:107], v[210:213], v[170:173], v[104:107]
	v_mfma_f32_16x16x32_bf16 v[96:99], v[202:205], v[178:181], v[96:99]
	v_mfma_f32_16x16x32_bf16 v[88:91], v[210:213], v[178:181], v[88:91]
	v_mfma_f32_16x16x32_bf16 v[80:83], v[202:205], v[186:189], v[80:83]
	v_mfma_f32_16x16x32_bf16 v[72:75], v[210:213], v[186:189], v[72:75]
	v_mfma_f32_16x16x32_bf16 v[68:71], v[202:205], v[194:197], v[68:71]
	v_mfma_f32_16x16x32_bf16 v[64:67], v[210:213], v[194:197], v[64:67]
	v_mfma_f32_16x16x32_bf16 v[112:115], v[206:209], v[174:177], v[112:115]
	ds_read_b128 v[170:173], v151 offset:16384
	v_mfma_f32_16x16x32_bf16 v[104:107], v[214:217], v[174:177], v[104:107]
	v_mfma_f32_16x16x32_bf16 v[96:99], v[206:209], v[182:185], v[96:99]
	ds_read_b128 v[178:181], v151 offset:18432
	v_mfma_f32_16x16x32_bf16 v[88:91], v[214:217], v[182:185], v[88:91]
	v_mfma_f32_16x16x32_bf16 v[80:83], v[206:209], v[190:193], v[80:83]
	ds_read_b128 v[186:189], v151 offset:20480
	v_mfma_f32_16x16x32_bf16 v[72:75], v[214:217], v[190:193], v[72:75]
	v_mfma_f32_16x16x32_bf16 v[68:71], v[206:209], v[198:201], v[68:71]
	ds_read_b128 v[194:197], v151 offset:22528
	v_mfma_f32_16x16x32_bf16 v[64:67], v[214:217], v[198:201], v[64:67]
	s_setprio 0
	s_mov_b32 m0, s57
	s_mov_b64 s[100:101], s[48:49]
	s_barrier
	ds_read_b128 v[174:177], v151 offset:17408
	ds_read_b128 v[182:185], v151 offset:19456
	ds_read_b128 v[190:193], v151 offset:21504
	ds_read_b128 v[198:201], v151 offset:23552
	global_load_lds_dwordx4 v134, s[48:49]
	s_mov_b32 m0, s58
	s_nop 0
	global_load_lds_dwordx4 v138, s[48:49]
	s_waitcnt vmcnt(8)
	s_barrier
	s_waitcnt lgkmcnt(0)
	s_setprio 1
	v_mfma_f32_16x16x32_bf16 v[60:63], v[154:157], v[170:173], v[60:63]
	v_mfma_f32_16x16x32_bf16 v[56:59], v[162:165], v[170:173], v[56:59]
	v_mfma_f32_16x16x32_bf16 v[52:55], v[154:157], v[178:181], v[52:55]
	v_mfma_f32_16x16x32_bf16 v[44:47], v[162:165], v[178:181], v[44:47]
	v_mfma_f32_16x16x32_bf16 v[36:39], v[154:157], v[186:189], v[36:39]
	v_mfma_f32_16x16x32_bf16 v[28:31], v[162:165], v[186:189], v[28:31]
	v_mfma_f32_16x16x32_bf16 v[20:23], v[154:157], v[194:197], v[20:23]
	v_mfma_f32_16x16x32_bf16 v[12:15], v[162:165], v[194:197], v[12:15]
	v_mfma_f32_16x16x32_bf16 v[60:63], v[158:161], v[174:177], v[60:63]
	v_mfma_f32_16x16x32_bf16 v[56:59], v[166:169], v[174:177], v[56:59]
	v_mfma_f32_16x16x32_bf16 v[52:55], v[158:161], v[182:185], v[52:55]
	v_mfma_f32_16x16x32_bf16 v[44:47], v[166:169], v[182:185], v[44:47]
	v_mfma_f32_16x16x32_bf16 v[36:39], v[158:161], v[190:193], v[36:39]
	v_mfma_f32_16x16x32_bf16 v[28:31], v[166:169], v[190:193], v[28:31]
	v_mfma_f32_16x16x32_bf16 v[20:23], v[158:161], v[198:201], v[20:23]
	v_mfma_f32_16x16x32_bf16 v[12:15], v[166:169], v[198:201], v[12:15]
	s_setprio 0
	s_barrier
	s_add_u32 s82, s46, 0x100000
	s_addc_u32 s83, s47, 0
	s_add_i32 s84, s67, s56
	s_mov_b32 m0, s84
	s_nop 0
	global_load_lds_dwordx4 v136, s[82:83]
	s_add_i32 m0, s84, 0x2000
	s_nop 0
	global_load_lds_dwordx4 v140, s[82:83]
	s_waitcnt vmcnt(6)
	s_barrier
	s_setprio 1
	v_add_u32_e32 v153, 0x18000, v148
	v_mfma_f32_16x16x32_bf16 v[48:51], v[202:205], v[170:173], v[48:51]
	ds_read_b128 v[154:157], v153
	v_mfma_f32_16x16x32_bf16 v[40:43], v[210:213], v[170:173], v[40:43]
	v_mfma_f32_16x16x32_bf16 v[32:35], v[202:205], v[178:181], v[32:35]
	ds_read_b128 v[158:161], v153 offset:1024
	v_mfma_f32_16x16x32_bf16 v[24:27], v[210:213], v[178:181], v[24:27]
	v_mfma_f32_16x16x32_bf16 v[16:19], v[202:205], v[186:189], v[16:19]
	ds_read_b128 v[162:165], v153 offset:2048
	v_mfma_f32_16x16x32_bf16 v[8:11], v[210:213], v[186:189], v[8:11]
	v_mfma_f32_16x16x32_bf16 v[4:7], v[202:205], v[194:197], v[4:7]
	ds_read_b128 v[166:169], v153 offset:3072
	v_mfma_f32_16x16x32_bf16 v[0:3], v[210:213], v[194:197], v[0:3]
	v_mfma_f32_16x16x32_bf16 v[48:51], v[206:209], v[174:177], v[48:51]
	ds_read_b128 v[170:173], v151 offset:32768
	v_mfma_f32_16x16x32_bf16 v[40:43], v[214:217], v[174:177], v[40:43]
	v_mfma_f32_16x16x32_bf16 v[32:35], v[206:209], v[182:185], v[32:35]
	ds_read_b128 v[178:181], v151 offset:34816
	v_mfma_f32_16x16x32_bf16 v[24:27], v[214:217], v[182:185], v[24:27]
	v_mfma_f32_16x16x32_bf16 v[16:19], v[206:209], v[190:193], v[16:19]
	ds_read_b128 v[186:189], v151 offset:36864
	v_mfma_f32_16x16x32_bf16 v[8:11], v[214:217], v[190:193], v[8:11]
	v_mfma_f32_16x16x32_bf16 v[4:7], v[206:209], v[198:201], v[4:7]
	ds_read_b128 v[194:197], v151 offset:38912
	v_mfma_f32_16x16x32_bf16 v[0:3], v[214:217], v[198:201], v[0:3]
	s_setprio 0
	s_add_i32 s82, 0, 0x18000
	v_add_u32_e32 v153, s82, v148
	s_barrier
	s_add_u32 s48, s48, 0x100000
	s_addc_u32 s49, s49, 0
	s_mov_b32 m0, s59
	ds_read_b128 v[174:177], v151 offset:33792
	ds_read_b128 v[182:185], v151 offset:35840
	ds_read_b128 v[190:193], v151 offset:37888
	ds_read_b128 v[198:201], v151 offset:39936
	global_load_lds_dwordx4 v134, s[48:49]
	s_mov_b32 m0, s60
	s_nop 0
	global_load_lds_dwordx4 v138, s[48:49]
	s_waitcnt lgkmcnt(8)
	s_barrier
; #define PG8_STAGE(bufoff, gbase, voff) do { _Pragma("unroll") for (int _i = 0; _i < 2; ++_i) \
;         __builtin_amdgcn_global_load_lds((const unsigned*)((const char*)(gbase) + (voff)[_i]), (LAS unsigned*)(lds + (bufoff) + ldsw + _i * 8192), 16, 0, 0); } while (0)
; #define PG8_LDA(dst, b, h) do { _Pragma("unroll") for (int m = 0; m < 4; ++m) _Pragma("unroll") for (int k = 0; k < 2; ++k) dst[m][k] = *(const LAS bf16x8*)(lds + PG8_SA(b, h) + aoff + m * 2048 + k * 1024); } while (0)
; #define PG8_LDB(dst, b, h) do { _Pragma("unroll") for (int n = 0; n < 2; ++n) _Pragma("unroll") for (int k = 0; k < 2; ++k) dst[n][k] = *(const LAS bf16x8*)(lds + PG8_SB(b, h) + boff + n * 2048 + k * 1024); } while (0)
; #define PG8_MMA(ai, bj, At, Bt) do { __builtin_amdgcn_s_setprio(1); _Pragma("unroll") for (int m = 0; m < 4; ++m) _Pragma("unroll") for (int n = 0; n < 2; ++n) _Pragma("unroll") for (int k = 0; k < 2; ++k) \
;         acc[ai][bj][m][n] = __builtin_amdgcn_mfma_f32_16x16x32_bf16(Bt[n][k], At[m][k], acc[ai][bj][m][n], 0, 0, 0); __builtin_amdgcn_s_setprio(0); } while (0)
; #define PG8_WAIT_V(n) asm volatile("s_waitcnt vmcnt(" #n ")" ::: "memory")
; #define PG8_WAIT_L(n) asm volatile("s_waitcnt lgkmcnt(" #n ")" ::: "memory")
; #define PG8_BAR __builtin_amdgcn_s_barrier()
; #define PG8_SCHED __builtin_amdgcn_sched_barrier(0)
; template <class Epi, class Job>
; __device__ __forceinline__ void gemm_phase(LAS unsigned char* lds, const Job& S, const Epi& E) {
;     ...
;             PG8_WAIT_L(8); PG8_BAR; PG8_WAIT_L(0); PG8_MMA(0, 0, At, B0); PG8_BAR; PG8_SCHED;
;             PG8_LDB(B1, 1, 1); PG8_STAGE(PG8_SB(1, 0), b3, voffB);
;             PG8_BAR; PG8_WAIT_L(0); PG8_MMA(0, 1, At, B1); PG8_BAR;
;             PG8_LDA(At, 1, 1); PG8_STAGE(PG8_SA(1, 0), a3, voffA);
;             PG8_BAR; PG8_WAIT_L(0); PG8_MMA(1, 0, At, B0); PG8_BAR; PG8_SCHED;
;             PG8_STAGE(PG8_SB(1, 1), b3 + hstepB, voffB);
;             PG8_WAIT_V(6); PG8_BAR; PG8_MMA(1, 1, At, B1); PG8_BAR;
	s_waitcnt lgkmcnt(0)
	s_setprio 1
	v_add_u32_e32 v153, 0x1c000, v148
	v_mfma_f32_16x16x32_bf16 v[124:127], v[154:157], v[170:173], v[124:127]
	ds_read_b128 v[202:205], v153
	v_mfma_f32_16x16x32_bf16 v[120:123], v[162:165], v[170:173], v[120:123]
	v_mfma_f32_16x16x32_bf16 v[116:119], v[154:157], v[178:181], v[116:119]
	ds_read_b128 v[206:209], v153 offset:1024
	v_mfma_f32_16x16x32_bf16 v[108:111], v[162:165], v[178:181], v[108:111]
	v_mfma_f32_16x16x32_bf16 v[100:103], v[154:157], v[186:189], v[100:103]
	ds_read_b128 v[210:213], v153 offset:2048
	v_mfma_f32_16x16x32_bf16 v[92:95], v[162:165], v[186:189], v[92:95]
	v_mfma_f32_16x16x32_bf16 v[84:87], v[154:157], v[194:197], v[84:87]
	ds_read_b128 v[214:217], v153 offset:3072
	v_mfma_f32_16x16x32_bf16 v[76:79], v[162:165], v[194:197], v[76:79]
	v_mfma_f32_16x16x32_bf16 v[124:127], v[158:161], v[174:177], v[124:127]
	v_mfma_f32_16x16x32_bf16 v[120:123], v[166:169], v[174:177], v[120:123]
	v_mfma_f32_16x16x32_bf16 v[116:119], v[158:161], v[182:185], v[116:119]
	v_mfma_f32_16x16x32_bf16 v[108:111], v[166:169], v[182:185], v[108:111]
	v_mfma_f32_16x16x32_bf16 v[100:103], v[158:161], v[190:193], v[100:103]
	v_mfma_f32_16x16x32_bf16 v[92:95], v[166:169], v[190:193], v[92:95]
	v_mfma_f32_16x16x32_bf16 v[84:87], v[158:161], v[198:201], v[84:87]
	v_mfma_f32_16x16x32_bf16 v[76:79], v[166:169], v[198:201], v[76:79]
	s_setprio 0
	s_barrier
	s_add_i32 s48, 0, 0x1c000
	s_add_i32 s49, s82, s56
	v_add_u32_e32 v153, s48, v148
	s_add_u32 s98, s46, s8
	s_addc_u32 s99, s47, s9
	s_mov_b32 m0, s49
	s_nop 0
	global_load_lds_dwordx4 v136, s[98:99]
	s_add_i32 m0, s49, 0x2000
	s_nop 0
	global_load_lds_dwordx4 v140, s[98:99]
	s_barrier
	s_waitcnt lgkmcnt(0)
	s_setprio 1
	v_mfma_f32_16x16x32_bf16 v[112:115], v[202:205], v[170:173], v[112:115]
	v_mfma_f32_16x16x32_bf16 v[104:107], v[210:213], v[170:173], v[104:107]
	v_mfma_f32_16x16x32_bf16 v[96:99], v[202:205], v[178:181], v[96:99]
	v_mfma_f32_16x16x32_bf16 v[88:91], v[210:213], v[178:181], v[88:91]
	v_mfma_f32_16x16x32_bf16 v[80:83], v[202:205], v[186:189], v[80:83]
	v_mfma_f32_16x16x32_bf16 v[72:75], v[210:213], v[186:189], v[72:75]
	v_mfma_f32_16x16x32_bf16 v[68:71], v[202:205], v[194:197], v[68:71]
	v_mfma_f32_16x16x32_bf16 v[64:67], v[210:213], v[194:197], v[64:67]
	v_mfma_f32_16x16x32_bf16 v[112:115], v[206:209], v[174:177], v[112:115]
	ds_read_b128 v[170:173], v151 offset:49152
	v_mfma_f32_16x16x32_bf16 v[104:107], v[214:217], v[174:177], v[104:107]
	v_mfma_f32_16x16x32_bf16 v[96:99], v[206:209], v[182:185], v[96:99]
	ds_read_b128 v[178:181], v151 offset:51200
	v_mfma_f32_16x16x32_bf16 v[88:91], v[214:217], v[182:185], v[88:91]
	v_mfma_f32_16x16x32_bf16 v[80:83], v[206:209], v[190:193], v[80:83]
	ds_read_b128 v[186:189], v151 offset:53248
	v_mfma_f32_16x16x32_bf16 v[72:75], v[214:217], v[190:193], v[72:75]
	v_mfma_f32_16x16x32_bf16 v[68:71], v[206:209], v[198:201], v[68:71]
	ds_read_b128 v[194:197], v151 offset:55296
	v_mfma_f32_16x16x32_bf16 v[64:67], v[214:217], v[198:201], v[64:67]
	s_setprio 0
	s_mov_b32 m0, s62
	s_add_u32 s100, s100, s8
	s_addc_u32 s101, s101, s9
	s_barrier
	ds_read_b128 v[174:177], v151 offset:50176
	ds_read_b128 v[182:185], v151 offset:52224
	ds_read_b128 v[190:193], v151 offset:54272
	ds_read_b128 v[198:201], v151 offset:56320
	global_load_lds_dwordx4 v134, s[100:101]
	s_mov_b32 m0, s63
	s_nop 0
	global_load_lds_dwordx4 v138, s[100:101]
	s_waitcnt vmcnt(8)
	s_barrier
	s_waitcnt lgkmcnt(0)
	s_setprio 1
	v_mfma_f32_16x16x32_bf16 v[60:63], v[154:157], v[170:173], v[60:63]
	v_mfma_f32_16x16x32_bf16 v[56:59], v[162:165], v[170:173], v[56:59]
	v_mfma_f32_16x16x32_bf16 v[52:55], v[154:157], v[178:181], v[52:55]
	v_mfma_f32_16x16x32_bf16 v[44:47], v[162:165], v[178:181], v[44:47]
	v_mfma_f32_16x16x32_bf16 v[36:39], v[154:157], v[186:189], v[36:39]
	v_mfma_f32_16x16x32_bf16 v[28:31], v[162:165], v[186:189], v[28:31]
	v_mfma_f32_16x16x32_bf16 v[20:23], v[154:157], v[194:197], v[20:23]
	v_mfma_f32_16x16x32_bf16 v[12:15], v[162:165], v[194:197], v[12:15]
	v_mfma_f32_16x16x32_bf16 v[60:63], v[158:161], v[174:177], v[60:63]
	v_mfma_f32_16x16x32_bf16 v[56:59], v[166:169], v[174:177], v[56:59]
	v_mfma_f32_16x16x32_bf16 v[52:55], v[158:161], v[182:185], v[52:55]
	v_mfma_f32_16x16x32_bf16 v[44:47], v[166:169], v[182:185], v[44:47]
	v_mfma_f32_16x16x32_bf16 v[36:39], v[158:161], v[190:193], v[36:39]
	v_mfma_f32_16x16x32_bf16 v[28:31], v[166:169], v[190:193], v[28:31]
	v_mfma_f32_16x16x32_bf16 v[20:23], v[158:161], v[198:201], v[20:23]
	v_mfma_f32_16x16x32_bf16 v[12:15], v[166:169], v[198:201], v[12:15]
	s_setprio 0
	s_barrier
	s_add_u32 s46, s46, 0x100080
	s_addc_u32 s47, s47, 0
	s_add_i32 s48, s48, s56
	s_mov_b32 m0, s48
	s_nop 0
	global_load_lds_dwordx4 v136, s[46:47]
	s_add_i32 m0, s48, 0x2000
	s_nop 0
	global_load_lds_dwordx4 v140, s[46:47]
	s_waitcnt vmcnt(6)
	s_barrier
; __device__ __forceinline__ unsigned cvt_pk_bf16(float lo, float hi) { unsigned r; asm volatile("v_cvt_pk_bf16_f32 %0, %1, %2" : "=v"(r) : "v"(lo), "v"(hi)); return r; }
; #define PG8_MMA(ai, bj, At, Bt) do { __builtin_amdgcn_s_setprio(1); _Pragma("unroll") for (int m = 0; m < 4; ++m) _Pragma("unroll") for (int n = 0; n < 2; ++n) _Pragma("unroll") for (int k = 0; k < 2; ++k) \
;         acc[ai][bj][m][n] = __builtin_amdgcn_mfma_f32_16x16x32_bf16(Bt[n][k], At[m][k], acc[ai][bj][m][n], 0, 0, 0); __builtin_amdgcn_s_setprio(0); } while (0)
; #define PG8_WAIT_V(n) asm volatile("s_waitcnt vmcnt(" #n ")" ::: "memory")
; #define PG8_BAR __builtin_amdgcn_s_barrier()
;     __device__ __forceinline__ void operator()(const f32x4 (&acc)[2][2][4][2], const Unit& u, int wr, int wc, int fr, int fq) const {
;         const int row0 = u.orow + wr * 64 + fr, col0 = u.ocol + wc * 32 + 8 * fq;
; #pragma unroll
;         for (int ai = 0; ai < 2; ++ai)
; #pragma unroll
;             for (int m = 0; m < 4; ++m) { bf16_t* rowp = O + (size_t)(row0 + ai * HALF + m * 16) * ldc + col0;
; #pragma unroll
;                 for (int bj = 0; bj < 2; ++bj) { const f32x4 v0 = acc[ai][bj][m][0], v1 = acc[ai][bj][m][1];
;                     u32x4 w; w.x = cvt_pk_bf16(v0[0], v0[1]); w.y = cvt_pk_bf16(v0[2], v0[3]); w.z = cvt_pk_bf16(v1[0], v1[1]); w.w = cvt_pk_bf16(v1[2], v1[3]);
;                     if (nt) __builtin_nontemporal_store(w, (u32x4*)(rowp + bj * HALF)); else *(u32x4*)(rowp + bj * HALF) = w; } }
; template <class Epi, class Job>
; __device__ __forceinline__ void gemm_phase(LAS unsigned char* lds, const Job& S, const Epi& E) {
;     ...
;             PG8_WAIT_V(6); PG8_BAR; PG8_MMA(1, 1, At, B1); PG8_BAR;
;         }
;         E(acc, cur, wr, wc, fr, fq);
;         if (!has_next) break;
	s_setprio 1
	v_mfma_f32_16x16x32_bf16 v[48:51], v[202:205], v[170:173], v[48:51]
	ds_read_b128 v[154:157], v150
	v_mfma_f32_16x16x32_bf16 v[40:43], v[210:213], v[170:173], v[40:43]
	v_mfma_f32_16x16x32_bf16 v[32:35], v[202:205], v[178:181], v[32:35]
	ds_read_b128 v[158:161], v150 offset:1024
	v_mfma_f32_16x16x32_bf16 v[24:27], v[210:213], v[178:181], v[24:27]
	v_mfma_f32_16x16x32_bf16 v[16:19], v[202:205], v[186:189], v[16:19]
	ds_read_b128 v[162:165], v150 offset:2048
	v_mfma_f32_16x16x32_bf16 v[8:11], v[210:213], v[186:189], v[8:11]
	v_mfma_f32_16x16x32_bf16 v[4:7], v[202:205], v[194:197], v[4:7]
	ds_read_b128 v[166:169], v150 offset:3072
	v_mfma_f32_16x16x32_bf16 v[0:3], v[210:213], v[194:197], v[0:3]
	v_mfma_f32_16x16x32_bf16 v[48:51], v[206:209], v[174:177], v[48:51]
	ds_read_b128 v[170:173], v151
	v_mfma_f32_16x16x32_bf16 v[40:43], v[214:217], v[174:177], v[40:43]
	v_mfma_f32_16x16x32_bf16 v[32:35], v[206:209], v[182:185], v[32:35]
	ds_read_b128 v[178:181], v151 offset:2048
	v_mfma_f32_16x16x32_bf16 v[24:27], v[214:217], v[182:185], v[24:27]
	v_mfma_f32_16x16x32_bf16 v[16:19], v[206:209], v[190:193], v[16:19]
	ds_read_b128 v[186:189], v151 offset:4096
	v_mfma_f32_16x16x32_bf16 v[8:11], v[214:217], v[190:193], v[8:11]
	v_mfma_f32_16x16x32_bf16 v[4:7], v[206:209], v[198:201], v[4:7]
	ds_read_b128 v[194:197], v151 offset:6144
	v_mfma_f32_16x16x32_bf16 v[0:3], v[214:217], v[198:201], v[0:3]
	s_setprio 0
	s_add_i32 s81, s81, 2
	s_add_u32 s36, s36, 0x100
	s_addc_u32 s37, s37, 0
	s_add_u32 s79, s79, 0x100
	s_addc_u32 s80, s80, 0
	s_cmp_gt_u32 s81, 61
	s_barrier
	s_cbranch_scc0 .LBB0_457
	s_waitcnt lgkmcnt(0)
	v_add_u32_e32 v146, s78, v131
	v_ashrrev_i32_e32 v147, 31, v146
	v_add_u32_e32 v154, s77, v149
	v_lshlrev_b64 v[146:147], 13, v[146:147]
	v_ashrrev_i32_e32 v155, 31, v154
	v_lshl_add_u64 v[146:147], s[18:19], 0, v[146:147]
	v_lshl_add_u64 v[146:147], v[154:155], 1, v[146:147]
	v_cvt_pk_bf16_f32 v124, v124, v125
	v_cvt_pk_bf16_f32 v125, v126, v127
	v_cvt_pk_bf16_f32 v126, v120, v121
	v_cvt_pk_bf16_f32 v127, v122, v123
	global_store_dwordx4 v[146:147], v[124:127], off
	v_cvt_pk_bf16_f32 v112, v112, v113
	v_cvt_pk_bf16_f32 v113, v114, v115
	v_cvt_pk_bf16_f32 v114, v104, v105
	v_cvt_pk_bf16_f32 v115, v106, v107
	global_store_dwordx4 v[146:147], v[112:115], off offset:256
	v_cvt_pk_bf16_f32 v104, v116, v117
	v_cvt_pk_bf16_f32 v105, v118, v119
	v_cvt_pk_bf16_f32 v106, v108, v109
	v_add_co_u32_e32 v108, vcc, s68, v146
	s_nop 0
	v_lshl_add_u64 v[112:113], v[146:147], 0, s[10:11]
	v_addc_co_u32_e32 v109, vcc, 0, v147, vcc
	v_cvt_pk_bf16_f32 v107, v110, v111
	global_store_dwordx4 v[108:109], v[104:107], off
	v_cvt_pk_bf16_f32 v96, v96, v97
	v_cvt_pk_bf16_f32 v97, v98, v99
	v_cvt_pk_bf16_f32 v98, v88, v89
	v_cvt_pk_bf16_f32 v99, v90, v91
	global_store_dwordx4 v[112:113], v[96:99], off offset:256
	v_cvt_pk_bf16_f32 v88, v100, v101
	v_cvt_pk_bf16_f32 v89, v102, v103
	v_cvt_pk_bf16_f32 v90, v92, v93
	v_add_co_u32_e32 v92, vcc, s69, v146
	s_nop 0
	v_lshl_add_u64 v[96:97], v[146:147], 0, s[12:13]
	v_addc_co_u32_e32 v93, vcc, 0, v147, vcc
	v_cvt_pk_bf16_f32 v91, v94, v95
	global_store_dwordx4 v[92:93], v[88:91], off
	v_cvt_pk_bf16_f32 v80, v80, v81
	v_cvt_pk_bf16_f32 v81, v82, v83
	v_cvt_pk_bf16_f32 v82, v72, v73
	v_cvt_pk_bf16_f32 v83, v74, v75
	global_store_dwordx4 v[96:97], v[80:83], off offset:256
	v_cvt_pk_bf16_f32 v72, v84, v85
	v_cvt_pk_bf16_f32 v73, v86, v87
	v_cvt_pk_bf16_f32 v74, v76, v77
	v_add_co_u32_e32 v76, vcc, s70, v146
	s_nop 0
	v_lshl_add_u64 v[80:81], v[146:147], 0, s[20:21]
	v_addc_co_u32_e32 v77, vcc, 0, v147, vcc
	v_cvt_pk_bf16_f32 v75, v78, v79
	global_store_dwordx4 v[76:77], v[72:75], off
	v_cvt_pk_bf16_f32 v68, v68, v69
	v_cvt_pk_bf16_f32 v69, v70, v71
	v_cvt_pk_bf16_f32 v70, v64, v65
	v_cvt_pk_bf16_f32 v71, v66, v67
	global_store_dwordx4 v[80:81], v[68:71], off offset:256
	v_cvt_pk_bf16_f32 v60, v60, v61
	v_cvt_pk_bf16_f32 v61, v62, v63
	v_cvt_pk_bf16_f32 v62, v56, v57
	v_add_co_u32_e32 v56, vcc, s71, v146
	v_lshl_add_u64 v[64:65], v[146:147], 0, s[6:7]
	s_nop 0
	v_addc_co_u32_e32 v57, vcc, 0, v147, vcc
	v_cvt_pk_bf16_f32 v63, v58, v59
	global_store_dwordx4 v[56:57], v[60:63], off
	v_cvt_pk_bf16_f32 v48, v48, v49
	v_cvt_pk_bf16_f32 v49, v50, v51
	v_cvt_pk_bf16_f32 v50, v40, v41
	v_cvt_pk_bf16_f32 v51, v42, v43
	global_store_dwordx4 v[64:65], v[48:51], off offset:256
	v_cvt_pk_bf16_f32 v40, v52, v53
	v_cvt_pk_bf16_f32 v41, v54, v55
	v_cvt_pk_bf16_f32 v42, v44, v45
	v_add_co_u32_e32 v44, vcc, s72, v146
	s_nop 0
	v_lshl_add_u64 v[48:49], v[146:147], 0, s[22:23]
	v_addc_co_u32_e32 v45, vcc, 0, v147, vcc
	v_cvt_pk_bf16_f32 v43, v46, v47
	global_store_dwordx4 v[44:45], v[40:43], off
	v_cvt_pk_bf16_f32 v32, v32, v33
	v_cvt_pk_bf16_f32 v33, v34, v35
	v_cvt_pk_bf16_f32 v34, v24, v25
	v_cvt_pk_bf16_f32 v35, v26, v27
	global_store_dwordx4 v[48:49], v[32:35], off offset:256
	v_cvt_pk_bf16_f32 v24, v36, v37
	v_cvt_pk_bf16_f32 v25, v38, v39
	v_cvt_pk_bf16_f32 v26, v28, v29
	v_add_co_u32_e32 v28, vcc, s73, v146
	s_nop 0
	v_lshl_add_u64 v[32:33], v[146:147], 0, s[24:25]
	v_addc_co_u32_e32 v29, vcc, 0, v147, vcc
	v_cvt_pk_bf16_f32 v27, v30, v31
	global_store_dwordx4 v[28:29], v[24:27], off
	v_cvt_pk_bf16_f32 v16, v16, v17
	v_cvt_pk_bf16_f32 v17, v18, v19
	v_cvt_pk_bf16_f32 v18, v8, v9
	v_cvt_pk_bf16_f32 v19, v10, v11
	global_store_dwordx4 v[32:33], v[16:19], off offset:256
	v_cvt_pk_bf16_f32 v8, v20, v21
	v_cvt_pk_bf16_f32 v9, v22, v23
	v_cvt_pk_bf16_f32 v10, v12, v13
	v_add_co_u32_e32 v12, vcc, s74, v146
	s_nop 0
	v_lshl_add_u64 v[16:17], v[146:147], 0, s[26:27]
	v_addc_co_u32_e32 v13, vcc, 0, v147, vcc
	s_and_b64 vcc, exec, s[4:5]
	s_mov_b32 s77, s76
	s_mov_b32 s78, s75
	s_mov_b64 s[46:47], s[30:31]
	s_mov_b64 s[36:37], s[28:29]
	v_cvt_pk_bf16_f32 v11, v14, v15
	global_store_dwordx4 v[12:13], v[8:11], off
	v_cvt_pk_bf16_f32 v4, v4, v5
	v_cvt_pk_bf16_f32 v5, v6, v7
	v_cvt_pk_bf16_f32 v6, v0, v1
	v_cvt_pk_bf16_f32 v7, v2, v3
	global_store_dwordx4 v[16:17], v[4:7], off offset:256
	s_cbranch_vccz .LBB0_450
	s_waitcnt vmcnt(0)
	s_cmpk_gt_u32 s50, 0xff
	s_cbranch_scc1 .LBB0_461
	s_barrier
